# deep (3-item) conversion pipeline at all sites incl. the G1/G5 idle tails, nt weight loads, 3200 items per tail
# speedup vs baseline: 1.0064x; 1.0064x over previous
.Lcv_site_p2:
	s_cmp_gt_u32 s98, 2
	s_cbranch_scc1 .Lcv_site_tail
	s_add_u32 s9, s30, 2
	s_mul_i32 s9, s9, 0x4180
	s_sub_u32 s8, s9, 0x4180
	s_cmp_eq_u32 s30, 0
	s_cselect_b32 s8, 0x1680, s8
	s_add_u32 s8, s8, s31
	s_mov_b32 s10, s66
	s_cmp_eq_u32 s3, 0x100
	s_cselect_b32 s32, 6400, 0
	s_sub_u32 s9, s9, s32
	s_branch .Lcv_go
.Lcv_site_tail:
	s_cmp_eq_u32 s3, 0x100
	s_cbranch_scc0 .Lcv_exit0
	s_cmp_lt_u32 s2, 216
	s_cbranch_scc1 .Lcv_exit0
	s_cmp_eq_u32 s98, 3
	s_cbranch_scc0 .Lcv_site_t5
	s_cmp_eq_u32 s30, 0
	s_cbranch_scc1 .Lcv_exit0
	s_add_u32 s9, s30, 1
	s_mul_i32 s9, s9, 0x4180
	s_sub_u32 s9, s9, 3200
	s_branch .Lcv_site_tc

.Lcv_site_tc:
	s_sub_u32 s8, s9, 3200
	s_sub_u32 s32, s2, 216
	s_lshl_b32 s32, s32, 3
	s_add_u32 s32, s32, s29
	s_add_u32 s8, s8, s32
	s_movk_i32 s10, 0x140
.Lcv_go:
	s_waitcnt lgkmcnt(0)
	s_add_u32 s6, s6, 0x100000
	s_addc_u32 s7, s7, 0
	s_cmp_ge_u32 s8, s9
	s_cbranch_scc1 .Lcv_exit
	s_mov_b32 s11, s8
	s_mov_b32 s12, 0
	s_mov_b32 s13, s11
	s_cmp_ge_u32 s13, 0x4180
	s_cbranch_scc0 .Lcv_d0_l
	s_sub_u32 s13, s13, 0x4180
	s_add_u32 s12, s12, 1
	s_cmp_ge_u32 s13, 0x4180
	s_cbranch_scc0 .Lcv_d0_l
	s_sub_u32 s13, s13, 0x4180
	s_add_u32 s12, s12, 1
	s_cmp_ge_u32 s13, 0x4180
	s_cbranch_scc0 .Lcv_d0_l
	s_sub_u32 s13, s13, 0x4180
	s_add_u32 s12, s12, 1
